# v19 plus spatial gating: W A-fragments ks=4,5 also prefetched at the loop top (B-fragment uses of their registers renamed to free quads)
# baseline (speedup 1.0000x reference)
; #define LAS __attribute__((address_space(3)))
; __device__ __forceinline__ unsigned cvtpk(float lo, float hi) { f32x2 v = {lo, hi}; bf16x2_t b = __builtin_convertvector(v, bf16x2_t); return __builtin_bit_cast(unsigned, b); }
; __device__ __forceinline__ float bflo(unsigned w) { return __uint_as_float(w << 16); }
; __device__ __forceinline__ float bfhi(unsigned w) { return __uint_as_float(w & 0xffff0000u); }
; __device__ __forceinline__ void spatial_unit(LAS unsigned char* lds, const Args& a, int b, int n, int ghalf, int tid, int wid, int lane) {
;     ...
;     for (int gi = 0; gi < 4; ++gi) {
;         const int g = ghalf * 4 + gi;
;         { const int lc = tid & 31, ch = g * 256 + lc * 8, row0 = tid >> 5;
;           u32x4 w[8];
; #pragma unroll
;           for (int it = 0; it < 8; ++it) w[it] = *(const u32x4*)(VSp + (size_t)(tok0 + row0 + it * 16) * DM + ch);
;           const f32x4 g0 = *(const f32x4*)(a.sg_ln_g + ch), g1 = *(const f32x4*)(a.sg_ln_g + ch + 4), b0 = *(const f32x4*)(a.sg_ln_b + ch), b1 = *(const f32x4*)(a.sg_ln_b + ch + 4);
; #pragma unroll
;           for (int it = 0; it < 8; ++it) { const int row = row0 + it * 16; const f32x2 st = stats[row];
;             u32x4 o;
;             o.x = cvtpk((bflo(w[it].x) - st.x) * st.y * g0[0] + b0[0], (bfhi(w[it].x) - st.x) * st.y * g0[1] + b0[1]);
;             o.y = cvtpk((bflo(w[it].y) - st.x) * st.y * g0[2] + b0[2], (bfhi(w[it].y) - st.x) * st.y * g0[3] + b0[3]);
;             o.z = cvtpk((bflo(w[it].z) - st.x) * st.y * g1[0] + b1[0], (bfhi(w[it].z) - st.x) * st.y * g1[1] + b1[1]);
;             o.w = cvtpk((bflo(w[it].w) - st.x) * st.y * g1[2] + b1[2], (bfhi(w[it].w) - st.x) * st.y * g1[3] + b1[3]);
;             *(LAS u32x4*)(lds + row * 512 + ((lc ^ ((row & 3) << 2)) << 4)) = o; } }
;         __syncthreads();
;         f32x16 acc[4];
; #pragma unroll
;         for (int d = 0; d < 4; ++d)
; #pragma unroll
;             for (int i = 0; i < 16; ++i) acc[d][i] = 0.f;
;         const bf16_t* wrow = Wb + (size_t)g * 16384 + (size_t)(ib * 32 + r) * 128 + 8 * h;
;         bf16x8 afr[8];
; #pragma unroll
;         for (int ks = 0; ks < 8; ++ks) afr[ks] = *(const bf16x8*)(wrow + 16 * ks);
.LBB0_520:
	global_load_dwordx4 v[220:223], v[72:73], off offset:-128
	global_load_dwordx4 v[224:227], v[72:73], off offset:-96
	global_load_dwordx4 v[228:231], v[72:73], off offset:-64
	global_load_dwordx4 v[232:235], v[72:73], off offset:-32
	global_load_dwordx4 v[170:173], v[72:73], off
	global_load_dwordx4 v[178:181], v[72:73], off offset:32
	global_load_dwordx4 v[0:3], v[90:91], off
	global_load_dwordx4 v[8:11], v[90:91], off offset:-16
	global_load_dwordx4 v[4:7], v[92:93], off
	global_load_dwordx4 v[12:15], v[92:93], off offset:-16
	v_lshl_add_u64 v[18:19], v[74:75], 0, s[0:1]
	v_lshl_add_u64 v[20:21], v[76:77], 0, s[0:1]
	v_lshl_add_u64 v[22:23], v[78:79], 0, s[0:1]
	v_lshl_add_u64 v[24:25], v[80:81], 0, s[0:1]
	v_lshl_add_u64 v[26:27], v[82:83], 0, s[0:1]
	v_lshl_add_u64 v[28:29], v[84:85], 0, s[0:1]
	v_lshl_add_u64 v[30:31], v[86:87], 0, s[0:1]
	v_lshl_add_u64 v[32:33], v[88:89], 0, s[0:1]
	ds_read_b64 v[16:17], v145
	global_load_dwordx4 v[34:37], v[18:19], off
	s_nop 0
	global_load_dwordx4 v[18:21], v[20:21], off
	s_nop 0
	global_load_dwordx4 v[38:41], v[22:23], off
	s_nop 0
	global_load_dwordx4 v[22:25], v[24:25], off
	s_nop 0
	global_load_dwordx4 v[42:45], v[26:27], off
	s_nop 0
	global_load_dwordx4 v[26:29], v[28:29], off
	s_nop 0
	global_load_dwordx4 v[46:49], v[30:31], off
	s_nop 0
	global_load_dwordx4 v[30:33], v[32:33], off
	v_add_u32_e32 v165, v154, v153
	v_lshl_add_u64 v[104:105], v[94:95], 0, s[0:1]
	v_lshl_add_u64 v[102:103], v[96:97], 0, s[0:1]
	v_lshl_add_u64 v[100:101], v[68:69], 0, s[0:1]
	v_lshl_add_u64 v[108:109], v[98:99], 0, s[0:1]
	v_lshl_add_u64 v[106:107], v[70:71], 0, s[0:1]
	v_lshl_add_u64 v[110:111], v[66:67], 0, s[0:1]
	s_add_u32 s0, s0, 0x200
	s_addc_u32 s1, s1, 0
	v_lshl_add_u64 v[90:91], v[90:91], 0, s[60:61]
	v_lshl_add_u64 v[92:93], v[92:93], 0, s[60:61]
	s_cmpk_lg_i32 s0, 0x800
	s_waitcnt vmcnt(7)
	v_lshlrev_b32_e32 v50, 16, v34
	v_and_b32_e32 v51, 0xffff0000, v34
	v_lshlrev_b32_e32 v34, 16, v35
	v_and_b32_e32 v35, 0xffff0000, v35
	v_lshlrev_b32_e32 v52, 16, v36
	v_and_b32_e32 v53, 0xffff0000, v36
	v_lshlrev_b32_e32 v36, 16, v37
	v_and_b32_e32 v37, 0xffff0000, v37
	s_waitcnt vmcnt(6)
	v_lshlrev_b32_e32 v54, 16, v18
	v_and_b32_e32 v55, 0xffff0000, v18
	v_lshlrev_b32_e32 v56, 16, v19
	v_and_b32_e32 v57, 0xffff0000, v19
	s_waitcnt lgkmcnt(0)
	v_pk_add_f32 v[18:19], v[50:51], v[16:17] op_sel_hi:[1,0] neg_lo:[0,1] neg_hi:[0,1]
	v_pk_add_f32 v[34:35], v[34:35], v[16:17] op_sel_hi:[1,0] neg_lo:[0,1] neg_hi:[0,1]
	v_pk_add_f32 v[50:51], v[52:53], v[16:17] op_sel_hi:[1,0] neg_lo:[0,1] neg_hi:[0,1]
	v_pk_add_f32 v[36:37], v[36:37], v[16:17] op_sel_hi:[1,0] neg_lo:[0,1] neg_hi:[0,1]
	v_pk_mul_f32 v[18:19], v[16:17], v[18:19] op_sel:[1,0]
	v_pk_mul_f32 v[34:35], v[16:17], v[34:35] op_sel:[1,0]
	v_pk_mul_f32 v[50:51], v[16:17], v[50:51] op_sel:[1,0]
	v_pk_mul_f32 v[16:17], v[16:17], v[36:37] op_sel:[1,0]
	v_pk_fma_f32 v[18:19], v[8:9], v[18:19], v[12:13]
	v_pk_fma_f32 v[34:35], v[10:11], v[34:35], v[14:15]
	v_pk_fma_f32 v[36:37], v[0:1], v[50:51], v[4:5]
	v_pk_fma_f32 v[50:51], v[2:3], v[16:17], v[6:7]
	v_cvt_pk_bf16_f32 v16, v18, v19
	v_cvt_pk_bf16_f32 v17, v34, v35
	v_cvt_pk_bf16_f32 v18, v36, v37
	v_cvt_pk_bf16_f32 v19, v50, v51
	ds_write_b128 v64, v[16:19]
	ds_read_b64 v[16:17], v146
	v_lshlrev_b32_e32 v58, 16, v20
	v_and_b32_e32 v59, 0xffff0000, v20
	v_lshlrev_b32_e32 v20, 16, v21
	v_and_b32_e32 v21, 0xffff0000, v21
	s_waitcnt lgkmcnt(0)
	v_pk_add_f32 v[18:19], v[54:55], v[16:17] op_sel_hi:[1,0] neg_lo:[0,1] neg_hi:[0,1]
	v_pk_add_f32 v[34:35], v[56:57], v[16:17] op_sel_hi:[1,0] neg_lo:[0,1] neg_hi:[0,1]
	v_pk_add_f32 v[36:37], v[58:59], v[16:17] op_sel_hi:[1,0] neg_lo:[0,1] neg_hi:[0,1]
	v_pk_add_f32 v[20:21], v[20:21], v[16:17] op_sel_hi:[1,0] neg_lo:[0,1] neg_hi:[0,1]
	v_pk_mul_f32 v[18:19], v[16:17], v[18:19] op_sel:[1,0]
	v_pk_mul_f32 v[34:35], v[16:17], v[34:35] op_sel:[1,0]
	v_pk_mul_f32 v[36:37], v[16:17], v[36:37] op_sel:[1,0]
	v_pk_mul_f32 v[16:17], v[16:17], v[20:21] op_sel:[1,0]
	v_pk_fma_f32 v[18:19], v[8:9], v[18:19], v[12:13]
	v_pk_fma_f32 v[20:21], v[10:11], v[34:35], v[14:15]
	v_pk_fma_f32 v[34:35], v[0:1], v[36:37], v[4:5]
	v_pk_fma_f32 v[36:37], v[2:3], v[16:17], v[6:7]
	v_cvt_pk_bf16_f32 v16, v18, v19
	v_cvt_pk_bf16_f32 v17, v20, v21
	v_cvt_pk_bf16_f32 v18, v34, v35
	v_cvt_pk_bf16_f32 v19, v36, v37
	ds_write_b128 v155, v[16:19]
	ds_read_b64 v[16:17], v147
	s_waitcnt vmcnt(5)
	v_lshlrev_b32_e32 v60, 16, v38
	v_and_b32_e32 v61, 0xffff0000, v38
	v_lshlrev_b32_e32 v38, 16, v39
	v_and_b32_e32 v39, 0xffff0000, v39
	v_lshlrev_b32_e32 v62, 16, v40
	v_and_b32_e32 v63, 0xffff0000, v40
	v_lshlrev_b32_e32 v40, 16, v41
	v_and_b32_e32 v41, 0xffff0000, v41
	s_waitcnt lgkmcnt(0)
	v_pk_add_f32 v[18:19], v[60:61], v[16:17] op_sel_hi:[1,0] neg_lo:[0,1] neg_hi:[0,1]
	v_pk_add_f32 v[20:21], v[38:39], v[16:17] op_sel_hi:[1,0] neg_lo:[0,1] neg_hi:[0,1]
	v_pk_add_f32 v[34:35], v[62:63], v[16:17] op_sel_hi:[1,0] neg_lo:[0,1] neg_hi:[0,1]
	v_pk_add_f32 v[36:37], v[40:41], v[16:17] op_sel_hi:[1,0] neg_lo:[0,1] neg_hi:[0,1]
	v_pk_mul_f32 v[18:19], v[16:17], v[18:19] op_sel:[1,0]
	v_pk_mul_f32 v[20:21], v[16:17], v[20:21] op_sel:[1,0]
	v_pk_mul_f32 v[34:35], v[16:17], v[34:35] op_sel:[1,0]
	v_pk_mul_f32 v[16:17], v[16:17], v[36:37] op_sel:[1,0]
	v_pk_fma_f32 v[18:19], v[8:9], v[18:19], v[12:13]
	v_pk_fma_f32 v[20:21], v[10:11], v[20:21], v[14:15]
	v_pk_fma_f32 v[34:35], v[0:1], v[34:35], v[4:5]
	v_pk_fma_f32 v[36:37], v[2:3], v[16:17], v[6:7]
	v_cvt_pk_bf16_f32 v16, v18, v19
	v_cvt_pk_bf16_f32 v17, v20, v21
	v_cvt_pk_bf16_f32 v18, v34, v35
	v_cvt_pk_bf16_f32 v19, v36, v37
	ds_write_b128 v156, v[16:19]
	ds_read_b64 v[16:17], v148
	s_waitcnt vmcnt(4)
; #define LAS __attribute__((address_space(3)))
; __device__ __forceinline__ unsigned cvtpk(float lo, float hi) { f32x2 v = {lo, hi}; bf16x2_t b = __builtin_convertvector(v, bf16x2_t); return __builtin_bit_cast(unsigned, b); }
; __device__ __forceinline__ float bflo(unsigned w) { return __uint_as_float(w << 16); }
; __device__ __forceinline__ float bfhi(unsigned w) { return __uint_as_float(w & 0xffff0000u); }
; __device__ __forceinline__ void spatial_unit(LAS unsigned char* lds, const Args& a, int b, int n, int ghalf, int tid, int wid, int lane) {
;     ...
;           for (int it = 0; it < 8; ++it) { const int row = row0 + it * 16; const f32x2 st = stats[row];
;             u32x4 o;
;             o.x = cvtpk((bflo(w[it].x) - st.x) * st.y * g0[0] + b0[0], (bfhi(w[it].x) - st.x) * st.y * g0[1] + b0[1]);
;             o.y = cvtpk((bflo(w[it].y) - st.x) * st.y * g0[2] + b0[2], (bfhi(w[it].y) - st.x) * st.y * g0[3] + b0[3]);
;             o.z = cvtpk((bflo(w[it].z) - st.x) * st.y * g1[0] + b1[0], (bfhi(w[it].z) - st.x) * st.y * g1[1] + b1[1]);
;             o.w = cvtpk((bflo(w[it].w) - st.x) * st.y * g1[2] + b1[2], (bfhi(w[it].w) - st.x) * st.y * g1[3] + b1[3]);
;             *(LAS u32x4*)(lds + row * 512 + ((lc ^ ((row & 3) << 2)) << 4)) = o; } }
;         __syncthreads();
	v_lshlrev_b32_e32 v112, 16, v22
	v_and_b32_e32 v113, 0xffff0000, v22
	v_lshlrev_b32_e32 v22, 16, v23
	v_and_b32_e32 v23, 0xffff0000, v23
	v_lshlrev_b32_e32 v114, 16, v24
	v_and_b32_e32 v115, 0xffff0000, v24
	v_lshlrev_b32_e32 v24, 16, v25
	v_and_b32_e32 v25, 0xffff0000, v25
	s_waitcnt lgkmcnt(0)
	v_pk_add_f32 v[18:19], v[112:113], v[16:17] op_sel_hi:[1,0] neg_lo:[0,1] neg_hi:[0,1]
	v_pk_add_f32 v[20:21], v[22:23], v[16:17] op_sel_hi:[1,0] neg_lo:[0,1] neg_hi:[0,1]
	v_pk_add_f32 v[22:23], v[114:115], v[16:17] op_sel_hi:[1,0] neg_lo:[0,1] neg_hi:[0,1]
	v_pk_add_f32 v[24:25], v[24:25], v[16:17] op_sel_hi:[1,0] neg_lo:[0,1] neg_hi:[0,1]
	v_pk_mul_f32 v[18:19], v[16:17], v[18:19] op_sel:[1,0]
	v_pk_mul_f32 v[20:21], v[16:17], v[20:21] op_sel:[1,0]
	v_pk_mul_f32 v[22:23], v[16:17], v[22:23] op_sel:[1,0]
	v_pk_mul_f32 v[16:17], v[16:17], v[24:25] op_sel:[1,0]
	v_pk_fma_f32 v[18:19], v[8:9], v[18:19], v[12:13]
	v_pk_fma_f32 v[20:21], v[10:11], v[20:21], v[14:15]
	v_pk_fma_f32 v[22:23], v[0:1], v[22:23], v[4:5]
	v_pk_fma_f32 v[24:25], v[2:3], v[16:17], v[6:7]
	v_cvt_pk_bf16_f32 v16, v18, v19
	v_cvt_pk_bf16_f32 v17, v20, v21
	v_cvt_pk_bf16_f32 v18, v22, v23
	v_cvt_pk_bf16_f32 v19, v24, v25
	ds_write_b128 v157, v[16:19]
	ds_read_b64 v[16:17], v149
	s_waitcnt vmcnt(3)
	v_lshlrev_b32_e32 v116, 16, v42
	v_and_b32_e32 v117, 0xffff0000, v42
	v_lshlrev_b32_e32 v42, 16, v43
	v_and_b32_e32 v43, 0xffff0000, v43
	v_lshlrev_b32_e32 v118, 16, v44
	v_and_b32_e32 v119, 0xffff0000, v44
	v_lshlrev_b32_e32 v44, 16, v45
	v_and_b32_e32 v45, 0xffff0000, v45
	s_waitcnt lgkmcnt(0)
	v_pk_add_f32 v[18:19], v[116:117], v[16:17] op_sel_hi:[1,0] neg_lo:[0,1] neg_hi:[0,1]
	v_pk_add_f32 v[20:21], v[42:43], v[16:17] op_sel_hi:[1,0] neg_lo:[0,1] neg_hi:[0,1]
	v_pk_add_f32 v[22:23], v[118:119], v[16:17] op_sel_hi:[1,0] neg_lo:[0,1] neg_hi:[0,1]
	v_pk_add_f32 v[24:25], v[44:45], v[16:17] op_sel_hi:[1,0] neg_lo:[0,1] neg_hi:[0,1]
	v_pk_mul_f32 v[18:19], v[16:17], v[18:19] op_sel:[1,0]
	v_pk_mul_f32 v[20:21], v[16:17], v[20:21] op_sel:[1,0]
	v_pk_mul_f32 v[22:23], v[16:17], v[22:23] op_sel:[1,0]
	v_pk_mul_f32 v[16:17], v[16:17], v[24:25] op_sel:[1,0]
	v_pk_fma_f32 v[18:19], v[8:9], v[18:19], v[12:13]
	v_pk_fma_f32 v[20:21], v[10:11], v[20:21], v[14:15]
	v_pk_fma_f32 v[22:23], v[0:1], v[22:23], v[4:5]
	v_pk_fma_f32 v[24:25], v[2:3], v[16:17], v[6:7]
	v_cvt_pk_bf16_f32 v16, v18, v19
	v_cvt_pk_bf16_f32 v17, v20, v21
	v_cvt_pk_bf16_f32 v18, v22, v23
	v_cvt_pk_bf16_f32 v19, v24, v25
	ds_write_b128 v158, v[16:19]
	ds_read_b64 v[16:17], v150
	s_waitcnt vmcnt(2)
	v_lshlrev_b32_e32 v120, 16, v26
	v_and_b32_e32 v121, 0xffff0000, v26
	v_lshlrev_b32_e32 v26, 16, v27
	v_and_b32_e32 v27, 0xffff0000, v27
	v_lshlrev_b32_e32 v122, 16, v28
	v_and_b32_e32 v123, 0xffff0000, v28
	v_lshlrev_b32_e32 v28, 16, v29
	v_and_b32_e32 v29, 0xffff0000, v29
	s_waitcnt lgkmcnt(0)
	v_pk_add_f32 v[18:19], v[120:121], v[16:17] op_sel_hi:[1,0] neg_lo:[0,1] neg_hi:[0,1]
	v_pk_add_f32 v[20:21], v[26:27], v[16:17] op_sel_hi:[1,0] neg_lo:[0,1] neg_hi:[0,1]
	v_pk_add_f32 v[22:23], v[122:123], v[16:17] op_sel_hi:[1,0] neg_lo:[0,1] neg_hi:[0,1]
	v_pk_add_f32 v[24:25], v[28:29], v[16:17] op_sel_hi:[1,0] neg_lo:[0,1] neg_hi:[0,1]
	v_pk_mul_f32 v[18:19], v[16:17], v[18:19] op_sel:[1,0]
	v_pk_mul_f32 v[20:21], v[16:17], v[20:21] op_sel:[1,0]
	v_pk_mul_f32 v[22:23], v[16:17], v[22:23] op_sel:[1,0]
	v_pk_mul_f32 v[16:17], v[16:17], v[24:25] op_sel:[1,0]
	v_pk_fma_f32 v[18:19], v[8:9], v[18:19], v[12:13]
	v_pk_fma_f32 v[20:21], v[10:11], v[20:21], v[14:15]
	v_pk_fma_f32 v[22:23], v[0:1], v[22:23], v[4:5]
	v_pk_fma_f32 v[24:25], v[2:3], v[16:17], v[6:7]
	v_cvt_pk_bf16_f32 v16, v18, v19
	v_cvt_pk_bf16_f32 v17, v20, v21
	v_cvt_pk_bf16_f32 v18, v22, v23
	v_cvt_pk_bf16_f32 v19, v24, v25
	ds_write_b128 v159, v[16:19]
	ds_read_b64 v[16:17], v151
	s_waitcnt vmcnt(1)
	v_lshlrev_b32_e32 v124, 16, v46
	v_and_b32_e32 v125, 0xffff0000, v46
	v_lshlrev_b32_e32 v46, 16, v47
	v_and_b32_e32 v47, 0xffff0000, v47
	v_lshlrev_b32_e32 v126, 16, v48
	v_and_b32_e32 v127, 0xffff0000, v48
	v_lshlrev_b32_e32 v48, 16, v49
	v_and_b32_e32 v49, 0xffff0000, v49
	s_waitcnt lgkmcnt(0)
	v_pk_add_f32 v[18:19], v[124:125], v[16:17] op_sel_hi:[1,0] neg_lo:[0,1] neg_hi:[0,1]
	v_pk_add_f32 v[20:21], v[46:47], v[16:17] op_sel_hi:[1,0] neg_lo:[0,1] neg_hi:[0,1]
	v_pk_add_f32 v[22:23], v[126:127], v[16:17] op_sel_hi:[1,0] neg_lo:[0,1] neg_hi:[0,1]
	v_pk_add_f32 v[24:25], v[48:49], v[16:17] op_sel_hi:[1,0] neg_lo:[0,1] neg_hi:[0,1]
	v_pk_mul_f32 v[18:19], v[16:17], v[18:19] op_sel:[1,0]
	v_pk_mul_f32 v[20:21], v[16:17], v[20:21] op_sel:[1,0]
	v_pk_mul_f32 v[22:23], v[16:17], v[22:23] op_sel:[1,0]
	v_pk_mul_f32 v[16:17], v[16:17], v[24:25] op_sel:[1,0]
	v_pk_fma_f32 v[18:19], v[8:9], v[18:19], v[12:13]
	v_pk_fma_f32 v[20:21], v[10:11], v[20:21], v[14:15]
	v_pk_fma_f32 v[22:23], v[0:1], v[22:23], v[4:5]
	v_pk_fma_f32 v[24:25], v[2:3], v[16:17], v[6:7]
	v_cvt_pk_bf16_f32 v16, v18, v19
	v_cvt_pk_bf16_f32 v17, v20, v21
	v_cvt_pk_bf16_f32 v18, v22, v23
	v_cvt_pk_bf16_f32 v19, v24, v25
	ds_write_b128 v160, v[16:19]
	ds_read_b64 v[16:17], v152
	s_waitcnt vmcnt(0)
	v_lshlrev_b32_e32 v128, 16, v30
	v_and_b32_e32 v129, 0xffff0000, v30
	v_lshlrev_b32_e32 v30, 16, v31
	v_and_b32_e32 v31, 0xffff0000, v31
	v_lshlrev_b32_e32 v130, 16, v32
	v_and_b32_e32 v131, 0xffff0000, v32
	v_lshlrev_b32_e32 v32, 16, v33
	v_and_b32_e32 v33, 0xffff0000, v33
	s_waitcnt lgkmcnt(0)
	v_pk_add_f32 v[18:19], v[128:129], v[16:17] op_sel_hi:[1,0] neg_lo:[0,1] neg_hi:[0,1]
	v_pk_add_f32 v[20:21], v[30:31], v[16:17] op_sel_hi:[1,0] neg_lo:[0,1] neg_hi:[0,1]
	v_pk_add_f32 v[22:23], v[130:131], v[16:17] op_sel_hi:[1,0] neg_lo:[0,1] neg_hi:[0,1]
	v_pk_add_f32 v[24:25], v[32:33], v[16:17] op_sel_hi:[1,0] neg_lo:[0,1] neg_hi:[0,1]
	v_pk_mul_f32 v[18:19], v[16:17], v[18:19] op_sel:[1,0]
	v_pk_mul_f32 v[20:21], v[16:17], v[20:21] op_sel:[1,0]
	v_pk_mul_f32 v[22:23], v[16:17], v[22:23] op_sel:[1,0]
	v_pk_mul_f32 v[16:17], v[16:17], v[24:25] op_sel:[1,0]
	v_pk_fma_f32 v[8:9], v[8:9], v[18:19], v[12:13]
	v_pk_fma_f32 v[10:11], v[10:11], v[20:21], v[14:15]
	v_pk_fma_f32 v[4:5], v[0:1], v[22:23], v[4:5]
	v_pk_fma_f32 v[6:7], v[2:3], v[16:17], v[6:7]
	v_cvt_pk_bf16_f32 v0, v8, v9
	v_cvt_pk_bf16_f32 v1, v10, v11
	v_cvt_pk_bf16_f32 v2, v4, v5
	v_cvt_pk_bf16_f32 v3, v6, v7
	ds_write_b128 v161, v[0:3]
	s_waitcnt lgkmcnt(0)
	s_barrier
; #define LAS __attribute__((address_space(3)))
; __device__ __forceinline__ s16x4 vtr(const LAS unsigned char* p) { return __builtin_bit_cast(s16x4, __builtin_amdgcn_ds_read_tr16_b64_v4i16((LAS v4i16_t*)p)); }
; #define MFMA32(a, b, c) __builtin_amdgcn_mfma_f32_32x32x16_bf16((a), (b), (c), 0, 0, 0)
; __device__ __forceinline__ void spatial_unit(LAS unsigned char* lds, const Args& a, int b, int n, int ghalf, int tid, int wid, int lane) {
;     ...
;         const bf16_t* wrow = Wb + (size_t)g * 16384 + (size_t)(ib * 32 + r) * 128 + 8 * h;
;         bf16x8 afr[8];
; #pragma unroll
;         for (int ks = 0; ks < 8; ++ks) afr[ks] = *(const bf16x8*)(wrow + 16 * ks);
; #pragma unroll
;         for (int ks = 0; ks < 8; ++ks) {
;             const bf16x8 af = afr[ks];
;             const LAS unsigned char* vb = lds + (16 * ks + 8 * h + tq) * 512 + (2 * g16 + (tp >> 1)) * 16 + (tp & 1) * 8;
; #pragma unroll
;             for (int d = 0; d < 4; ++d) { const int db = dbh * 4 + d;
;                 const LAS unsigned char* vp = vb + (((db ^ tq) & 3) << 6) + (db >> 2) * 256;
;                 const s16x4 lo = vtr(vp), hi = vtr(vp + 4 * 512);
;                 const bf16x8 bfr = __builtin_shufflevector(lo, hi, 0, 1, 2, 3, 4, 5, 6, 7);
;                 acc[d] = MFMA32(af, bfr, acc[d]); }
;         }
	s_nop 0
	s_nop 0
	ds_read_b64_tr_b16 v[0:1], v165
	ds_read_b64_tr_b16 v[2:3], v165 offset:2048
	ds_read_b64_tr_b16 v[118:119], v165 offset:8192
	ds_read_b64_tr_b16 v[120:121], v165 offset:10240
	s_waitcnt vmcnt(1) lgkmcnt(2)
	v_mfma_f32_32x32x16_bf16 v[0:15], v[220:223], v[0:3], 0
	ds_read_b64_tr_b16 v[16:17], v162
	ds_read_b64_tr_b16 v[18:19], v162 offset:2048
	ds_read_b64_tr_b16 v[122:123], v162 offset:8192
	ds_read_b64_tr_b16 v[124:125], v162 offset:10240
	ds_read_b64_tr_b16 v[32:33], v163
	ds_read_b64_tr_b16 v[34:35], v163 offset:2048
	ds_read_b64_tr_b16 v[166:167], v163 offset:8192
	ds_read_b64_tr_b16 v[168:169], v163 offset:10240
	ds_read_b64_tr_b16 v[52:53], v164
	ds_read_b64_tr_b16 v[54:55], v164 offset:2048
	ds_read_b64_tr_b16 v[236:237], v164 offset:8192
	ds_read_b64_tr_b16 v[238:239], v164 offset:10240
	v_add_co_u32_e32 v128, vcc, s57, v104
	s_nop 1
	v_addc_co_u32_e32 v129, vcc, 0, v105, vcc
	s_waitcnt lgkmcnt(6)
	v_mfma_f32_32x32x16_bf16 v[32:47], v[220:223], v[32:35], 0
	v_add_co_u32_e32 v134, vcc, s64, v104
	s_nop 1
	v_addc_co_u32_e32 v135, vcc, 0, v105, vcc
	v_add_co_u32_e32 v132, vcc, s35, v104
	s_waitcnt vmcnt(0)
	v_mfma_f32_32x32x16_bf16 v[0:15], v[224:227], v[118:121], v[0:15]
	s_nop 0
	v_addc_co_u32_e32 v133, vcc, 0, v105, vcc
	v_add_co_u32_e32 v130, vcc, s57, v102
	s_nop 1
	v_addc_co_u32_e32 v131, vcc, 0, v103, vcc
	s_waitcnt lgkmcnt(4)
	v_mfma_f32_32x32x16_bf16 v[32:47], v[224:227], v[166:169], v[32:47]
	s_nop 0
	v_add_co_u32_e32 v126, vcc, s64, v102
	s_nop 1
	v_addc_co_u32_e32 v127, vcc, 0, v103, vcc
	v_mfma_f32_32x32x16_bf16 v[16:31], v[220:223], v[16:19], 0
	s_waitcnt lgkmcnt(2)
	v_mfma_f32_32x32x16_bf16 v[48:63], v[220:223], v[52:55], 0
	v_mfma_f32_32x32x16_bf16 v[16:31], v[224:227], v[122:125], v[16:31]
	v_add_co_u32_e32 v124, vcc, s35, v102
	s_nop 1
	v_addc_co_u32_e32 v125, vcc, 0, v103, vcc
	v_add_co_u32_e32 v112, vcc, s57, v108
	s_waitcnt lgkmcnt(0)
	v_mfma_f32_32x32x16_bf16 v[48:63], v[224:227], v[236:239], v[48:63]
	ds_read_b64_tr_b16 v[114:115], v165 offset:16384
	ds_read_b64_tr_b16 v[116:117], v165 offset:18432
	ds_read_b64_tr_b16 v[236:237], v165 offset:24576
	ds_read_b64_tr_b16 v[238:239], v165 offset:26624
	ds_read_b64_tr_b16 v[220:221], v162 offset:16384
	ds_read_b64_tr_b16 v[222:223], v162 offset:18432
	ds_read_b64_tr_b16 v[182:183], v162 offset:24576
	ds_read_b64_tr_b16 v[184:185], v162 offset:26624
	v_addc_co_u32_e32 v113, vcc, 0, v109, vcc
	s_waitcnt vmcnt(1) lgkmcnt(6)
	v_mfma_f32_32x32x16_bf16 v[0:15], v[228:231], v[114:117], v[0:15]
	v_add_co_u32_e32 v114, vcc, s64, v108
	s_nop 1
	v_addc_co_u32_e32 v115, vcc, 0, v109, vcc
	v_add_co_u32_e32 v122, vcc, s35, v108
	s_waitcnt lgkmcnt(2)
	v_mfma_f32_32x32x16_bf16 v[16:31], v[228:231], v[220:223], v[16:31]
	ds_read_b64_tr_b16 v[220:221], v163 offset:16384
	ds_read_b64_tr_b16 v[222:223], v163 offset:18432
	ds_read_b64_tr_b16 v[186:187], v163 offset:24576
	ds_read_b64_tr_b16 v[188:189], v163 offset:26624
	v_addc_co_u32_e32 v123, vcc, 0, v109, vcc
	s_waitcnt lgkmcnt(2)
	v_mfma_f32_32x32x16_bf16 v[32:47], v[228:231], v[220:223], v[32:47]
	ds_read_b64_tr_b16 v[220:221], v164 offset:16384
	ds_read_b64_tr_b16 v[222:223], v164 offset:18432
	ds_read_b64_tr_b16 v[190:191], v164 offset:24576
	ds_read_b64_tr_b16 v[192:193], v164 offset:26624
	s_waitcnt vmcnt(0)
	v_mfma_f32_32x32x16_bf16 v[0:15], v[232:235], v[236:239], v[0:15]
	s_nop 0
	s_waitcnt lgkmcnt(2)
	v_mfma_f32_32x32x16_bf16 v[48:63], v[228:231], v[220:223], v[48:63]
	s_nop 0
	v_add_co_u32_e32 v120, vcc, s57, v106
	s_nop 1
	v_addc_co_u32_e32 v121, vcc, 0, v107, vcc
	v_add_co_u32_e32 v118, vcc, s64, v106
	v_mfma_f32_32x32x16_bf16 v[16:31], v[232:235], v[182:185], v[16:31]
	s_nop 0
	v_addc_co_u32_e32 v119, vcc, 0, v107, vcc
	v_add_co_u32_e32 v116, vcc, s35, v106
	s_nop 1
	v_addc_co_u32_e32 v117, vcc, 0, v107, vcc
	v_mfma_f32_32x32x16_bf16 v[32:47], v[232:235], v[186:189], v[32:47]
	s_waitcnt lgkmcnt(0)
	v_mfma_f32_32x32x16_bf16 v[48:63], v[232:235], v[190:193], v[48:63]
	global_load_dwordx4 v[166:169], v[72:73], off offset:64
	ds_read_b64_tr_b16 v[182:183], v165 offset:32768
	ds_read_b64_tr_b16 v[184:185], v165 offset:34816
	ds_read_b64_tr_b16 v[186:187], v165 offset:40960
	ds_read_b64_tr_b16 v[188:189], v165 offset:43008
	s_waitcnt vmcnt(2) lgkmcnt(2)
	v_mfma_f32_32x32x16_bf16 v[0:15], v[170:173], v[182:185], v[0:15]
	global_load_dwordx4 v[182:185], v[72:73], off offset:96
	ds_read_b64_tr_b16 v[190:191], v162 offset:32768
	ds_read_b64_tr_b16 v[192:193], v162 offset:34816
	ds_read_b64_tr_b16 v[194:195], v163 offset:32768
	ds_read_b64_tr_b16 v[196:197], v163 offset:34816
	ds_read_b64_tr_b16 v[200:201], v162 offset:40960
	ds_read_b64_tr_b16 v[202:203], v162 offset:43008
	v_lshl_add_u64 v[72:73], v[72:73], 0, s[58:59]
	s_waitcnt lgkmcnt(4)
; #define LAS __attribute__((address_space(3)))
; __device__ __forceinline__ s16x4 vtr(const LAS unsigned char* p) { return __builtin_bit_cast(s16x4, __builtin_amdgcn_ds_read_tr16_b64_v4i16((LAS v4i16_t*)p)); }
; #define MFMA32(a, b, c) __builtin_amdgcn_mfma_f32_32x32x16_bf16((a), (b), (c), 0, 0, 0)
; __device__ __forceinline__ void spatial_unit(LAS unsigned char* lds, const Args& a, int b, int n, int ghalf, int tid, int wid, int lane) {
;     ...
;         for (int ks = 0; ks < 8; ++ks) afr[ks] = *(const bf16x8*)(wrow + 16 * ks);
; #pragma unroll
;         for (int ks = 0; ks < 8; ++ks) {
;             const bf16x8 af = afr[ks];
;             const LAS unsigned char* vb = lds + (16 * ks + 8 * h + tq) * 512 + (2 * g16 + (tp >> 1)) * 16 + (tp & 1) * 8;
; #pragma unroll
;             for (int d = 0; d < 4; ++d) { const int db = dbh * 4 + d;
;                 const LAS unsigned char* vp = vb + (((db ^ tq) & 3) << 6) + (db >> 2) * 256;
;                 const s16x4 lo = vtr(vp), hi = vtr(vp + 4 * 512);
;                 const bf16x8 bfr = __builtin_shufflevector(lo, hi, 0, 1, 2, 3, 4, 5, 6, 7);
;                 acc[d] = MFMA32(af, bfr, acc[d]); }
;         }
; #pragma unroll
;         for (int hh2 = 0; hh2 < 2; ++hh2) {
;             bf16_t uv[8][4]; float bias[8];
; #pragma unroll
;             for (int ii = 0; ii < 8; ++ii) { const int i = hh2 * 8 + ii, il = ib * 32 + (i & 3) + 8 * (i >> 2) + 4 * h; bias[ii] = a.sg_b[g * 128 + il];
;                 const size_t off = (size_t)(tok0 + il) * DM + g * 256 + dbh * 128 + r;
; #pragma unroll
;                 for (int d = 0; d < 4; ++d) uv[ii][d] = Up[off + 32 * d]; }
	v_mfma_f32_32x32x16_bf16 v[16:31], v[170:173], v[190:193], v[16:31]
	ds_read_b64_tr_b16 v[190:191], v163 offset:40960
	ds_read_b64_tr_b16 v[192:193], v163 offset:43008
	ds_read_b64_tr_b16 v[204:205], v164 offset:32768
	ds_read_b64_tr_b16 v[206:207], v164 offset:34816
	ds_read_b64_tr_b16 v[208:209], v164 offset:40960
	ds_read_b64_tr_b16 v[210:211], v164 offset:43008
	global_load_ushort v174, v[104:105], off
	global_load_ushort v175, v[104:105], off offset:64
	global_load_ushort v199, v[104:105], off offset:128
	global_load_ushort v212, v[104:105], off offset:192
	global_load_ushort v213, v[134:135], off offset:-4096
	global_load_ushort v214, v[128:129], off offset:64
	global_load_ushort v215, v[128:129], off offset:128
	global_load_ushort v216, v[128:129], off offset:192
	global_load_ushort v217, v[134:135], off
	global_load_ushort v218, v[134:135], off offset:64
	global_load_ushort v219, v[134:135], off offset:128
	global_load_ushort v220, v[134:135], off offset:192
	global_load_ushort v221, v[132:133], off
	global_load_ushort v222, v[132:133], off offset:64
	global_load_ushort v223, v[132:133], off offset:128
	global_load_ushort v224, v[132:133], off offset:192
	global_load_ushort v225, v[102:103], off
	global_load_ushort v226, v[102:103], off offset:64
	global_load_ushort v227, v[102:103], off offset:128
	global_load_ushort v228, v[102:103], off offset:192
	global_load_ushort v229, v[126:127], off offset:-4096
	global_load_ushort v230, v[130:131], off offset:64
	global_load_ushort v231, v[130:131], off offset:128
	global_load_ushort v232, v[130:131], off offset:192
	global_load_ushort v233, v[126:127], off
	global_load_ushort v234, v[126:127], off offset:64
	global_load_ushort v235, v[126:127], off offset:128
	global_load_ushort v236, v[126:127], off offset:192
	global_load_ushort v237, v[124:125], off
	global_load_ushort v238, v[124:125], off offset:64
	global_load_ushort v239, v[124:125], off offset:128
	global_load_ushort v240, v[124:125], off offset:192
	s_waitcnt lgkmcnt(8)
	v_mfma_f32_32x32x16_bf16 v[32:47], v[170:173], v[194:197], v[32:47]
	s_waitcnt lgkmcnt(2)
	v_mfma_f32_32x32x16_bf16 v[48:63], v[170:173], v[204:207], v[48:63]
	global_load_dwordx4 v[170:173], v[100:101], off
	s_waitcnt vmcnt(35)
	v_mfma_f32_32x32x16_bf16 v[0:15], v[178:181], v[186:189], v[0:15]
	v_mfma_f32_32x32x16_bf16 v[16:31], v[178:181], v[200:203], v[16:31]
	v_mfma_f32_32x32x16_bf16 v[32:47], v[178:181], v[190:193], v[32:47]
	s_waitcnt lgkmcnt(0)
	v_mfma_f32_32x32x16_bf16 v[48:63], v[178:181], v[208:211], v[48:63]
	ds_read_b64_tr_b16 v[178:179], v165 offset:49152
	ds_read_b64_tr_b16 v[180:181], v165 offset:51200
	ds_read_b64_tr_b16 v[186:187], v165 offset:57344
	ds_read_b64_tr_b16 v[188:189], v165 offset:59392
	s_waitcnt vmcnt(32)
	v_lshlrev_b32_e32 v165, 16, v174
	s_waitcnt lgkmcnt(2)
	v_mfma_f32_32x32x16_bf16 v[0:15], v[166:169], v[178:181], v[0:15]
	global_load_dwordx4 v[178:181], v[100:101], off offset:32
	ds_read_b64_tr_b16 v[190:191], v162 offset:49152
	ds_read_b64_tr_b16 v[192:193], v162 offset:51200
	ds_read_b64_tr_b16 v[194:195], v162 offset:57344
	ds_read_b64_tr_b16 v[196:197], v162 offset:59392
	s_waitcnt vmcnt(32)
	v_lshlrev_b32_e32 v174, 16, v175
	s_waitcnt vmcnt(31)
	v_lshlrev_b32_e32 v175, 16, v199
	s_waitcnt vmcnt(18)
	v_lshlrev_b32_e32 v199, 16, v224
	s_waitcnt lgkmcnt(2)
	v_mfma_f32_32x32x16_bf16 v[16:31], v[166:169], v[190:193], v[16:31]
	ds_read_b64_tr_b16 v[190:191], v163 offset:49152
	ds_read_b64_tr_b16 v[192:193], v163 offset:51200
	ds_read_b64_tr_b16 v[200:201], v163 offset:57344
	ds_read_b64_tr_b16 v[202:203], v163 offset:59392
	ds_read_b64_tr_b16 v[204:205], v164 offset:49152
	ds_read_b64_tr_b16 v[206:207], v164 offset:51200
	ds_read_b64_tr_b16 v[208:209], v164 offset:57344
	ds_read_b64_tr_b16 v[210:211], v164 offset:59392
	s_waitcnt lgkmcnt(6)
	v_mfma_f32_32x32x16_bf16 v[32:47], v[166:169], v[190:193], v[32:47]
	v_lshlrev_b32_e32 v190, 16, v212
	v_lshlrev_b32_e32 v191, 16, v217
	v_lshlrev_b32_e32 v192, 16, v218
	v_lshlrev_b32_e32 v193, 16, v219
	s_waitcnt vmcnt(9)
	v_lshlrev_b32_e32 v212, 16, v233
	s_waitcnt lgkmcnt(2)
	v_mfma_f32_32x32x16_bf16 v[48:63], v[166:169], v[204:207], v[48:63]
	v_lshlrev_b32_e32 v166, 16, v213
	v_lshlrev_b32_e32 v167, 16, v214
	v_lshlrev_b32_e32 v168, 16, v215
	v_lshlrev_b32_e32 v169, 16, v216
	v_lshlrev_b32_e32 v204, 16, v225
	v_lshlrev_b32_e32 v205, 16, v226
	v_lshlrev_b32_e32 v206, 16, v231
	v_mfma_f32_32x32x16_bf16 v[0:15], v[182:185], v[186:189], v[0:15]
	v_lshlrev_b32_e32 v186, 16, v220
	v_lshlrev_b32_e32 v187, 16, v221
	v_lshlrev_b32_e32 v188, 16, v222
	v_lshlrev_b32_e32 v189, 16, v223
	v_lshlrev_b32_e32 v207, 16, v232
	s_waitcnt vmcnt(4)
	v_lshlrev_b32_e32 v213, 16, v238
	s_waitcnt vmcnt(3)
	v_lshlrev_b32_e32 v214, 16, v239
	v_mfma_f32_32x32x16_bf16 v[16:31], v[182:185], v[194:197], v[16:31]
	s_waitcnt vmcnt(1)
	s_nop 0
	v_add_f32_e32 v0, v0, v170
	v_lshlrev_b32_e32 v194, 16, v227
	v_lshlrev_b32_e32 v195, 16, v228
	v_lshlrev_b32_e32 v196, 16, v229
	v_lshlrev_b32_e32 v197, 16, v230
	v_lshlrev_b32_e32 v215, 16, v240
	v_add_f32_e32 v1, v1, v171
	v_mfma_f32_32x32x16_bf16 v[32:47], v[182:185], v[200:203], v[32:47]
	v_lshlrev_b32_e32 v200, 16, v234
	v_lshlrev_b32_e32 v201, 16, v235
	v_lshlrev_b32_e32 v202, 16, v236
	v_lshlrev_b32_e32 v203, 16, v237
	v_add_f32_e32 v16, v16, v170
	v_add_f32_e32 v17, v17, v171
	v_add_f32_e32 v2, v2, v172
	s_waitcnt lgkmcnt(0)
; __device__ __forceinline__ unsigned cvtpk(float lo, float hi) { f32x2 v = {lo, hi}; bf16x2_t b = __builtin_convertvector(v, bf16x2_t); return __builtin_bit_cast(unsigned, b); }
; __device__ __forceinline__ float bf2f(bf16_t b) { return __uint_as_float(((unsigned)b) << 16); }
; __device__ __forceinline__ void spatial_unit(LAS unsigned char* lds, const Args& a, int b, int n, int ghalf, int tid, int wid, int lane) {
;     ...
; #pragma unroll
;         for (int hh2 = 0; hh2 < 2; ++hh2) {
;             bf16_t uv[8][4]; float bias[8];
; #pragma unroll
;             for (int ii = 0; ii < 8; ++ii) { const int i = hh2 * 8 + ii, il = ib * 32 + (i & 3) + 8 * (i >> 2) + 4 * h; bias[ii] = a.sg_b[g * 128 + il];
;                 const size_t off = (size_t)(tok0 + il) * DM + g * 256 + dbh * 128 + r;
; #pragma unroll
;                 for (int d = 0; d < 4; ++d) uv[ii][d] = Up[off + 32 * d]; }
;             asm volatile("" ::: "memory");
; #pragma unroll
;             for (int ii = 0; ii < 8; ++ii) { const int i = hh2 * 8 + ii, il = ib * 32 + (i & 3) + 8 * (i >> 2) + 4 * h;
;                 const size_t off = (size_t)(tok0 + il) * DM + g * 256 + dbh * 128 + r;
; #pragma unroll
;                 for (int d = 0; d < 4; ++d) Up[off + 32 * d] = (bf16_t)(cvtpk(bf2f(uv[ii][d]) * (acc[d][i] + bias[ii]), 0.f) & 0xffffu); }
	v_mfma_f32_32x32x16_bf16 v[48:63], v[182:185], v[208:211], v[48:63]
	s_nop 2
	v_add_f32_e32 v32, v32, v170
	v_add_f32_e32 v33, v33, v171
	v_add_f32_e32 v18, v18, v172
	v_add_f32_e32 v34, v34, v172
	v_add_f32_e32 v3, v3, v173
	v_add_f32_e32 v19, v19, v173
	v_add_f32_e32 v35, v35, v173
	s_nop 1
	v_add_f32_e32 v48, v48, v170
	v_add_f32_e32 v49, v49, v171
	v_add_f32_e32 v50, v50, v172
	v_add_f32_e32 v51, v51, v173
	v_mul_f32_e32 v0, v0, v165
	v_mul_f32_e32 v16, v16, v174
	v_mul_f32_e32 v32, v32, v175
	v_mul_f32_e32 v48, v48, v190
	v_mul_f32_e32 v1, v1, v166
	v_mul_f32_e32 v17, v17, v167
	v_mul_f32_e32 v33, v33, v168
	v_mul_f32_e32 v49, v49, v169
	v_mul_f32_e32 v2, v2, v191
	v_mul_f32_e32 v18, v18, v192
	v_mul_f32_e32 v34, v34, v193
	v_mul_f32_e32 v50, v50, v186
	v_mul_f32_e32 v3, v3, v187
	s_waitcnt vmcnt(0)
	v_add_f32_e32 v4, v4, v178
	v_add_f32_e32 v20, v20, v178
	v_add_f32_e32 v36, v36, v178
	v_add_f32_e32 v52, v52, v178
	v_add_f32_e32 v5, v5, v179
	v_add_f32_e32 v21, v21, v179
	v_add_f32_e32 v37, v37, v179
	v_add_f32_e32 v53, v53, v179
	v_add_f32_e32 v6, v6, v180
	v_add_f32_e32 v22, v22, v180
	v_add_f32_e32 v38, v38, v180
	v_add_f32_e32 v54, v54, v180
	v_add_f32_e32 v7, v7, v181
	v_add_f32_e32 v23, v23, v181
	v_add_f32_e32 v39, v39, v181
	v_add_f32_e32 v55, v55, v181
	v_mul_f32_e32 v19, v19, v188
	v_mul_f32_e32 v35, v35, v189
	v_mul_f32_e32 v51, v51, v199
	v_mul_f32_e32 v4, v4, v204
	v_mul_f32_e32 v20, v20, v205
	v_mul_f32_e32 v36, v36, v194
	v_mul_f32_e32 v52, v52, v195
	v_mul_f32_e32 v5, v5, v196
	v_mul_f32_e32 v21, v21, v197
	v_mul_f32_e32 v37, v37, v206
	v_mul_f32_e32 v53, v53, v207
	v_mul_f32_e32 v6, v6, v212
	v_mul_f32_e32 v22, v22, v200
	v_mul_f32_e32 v38, v38, v201
	v_mul_f32_e32 v54, v54, v202
	v_mul_f32_e32 v7, v7, v203
	v_mul_f32_e32 v23, v23, v213
	v_mul_f32_e32 v39, v39, v214
	v_mul_f32_e32 v55, v55, v215
	v_cvt_pk_bf16_f32 v0, v0, s0
	v_cvt_pk_bf16_f32 v16, v16, s0
	v_cvt_pk_bf16_f32 v32, v32, s0
	v_cvt_pk_bf16_f32 v48, v48, s0
	v_cvt_pk_bf16_f32 v1, v1, s0
	v_cvt_pk_bf16_f32 v17, v17, s0
	v_cvt_pk_bf16_f32 v33, v33, s0
	v_cvt_pk_bf16_f32 v49, v49, s0
	v_cvt_pk_bf16_f32 v2, v2, s0
	v_cvt_pk_bf16_f32 v18, v18, s0
	v_cvt_pk_bf16_f32 v34, v34, s0
	v_cvt_pk_bf16_f32 v50, v50, s0
	v_cvt_pk_bf16_f32 v3, v3, s0
	v_cvt_pk_bf16_f32 v19, v19, s0
	v_cvt_pk_bf16_f32 v35, v35, s0
	v_cvt_pk_bf16_f32 v51, v51, s0
	v_cvt_pk_bf16_f32 v4, v4, s0
	v_cvt_pk_bf16_f32 v20, v20, s0
	v_cvt_pk_bf16_f32 v36, v36, s0
	v_cvt_pk_bf16_f32 v52, v52, s0
	v_cvt_pk_bf16_f32 v5, v5, s0
	v_cvt_pk_bf16_f32 v21, v21, s0
	v_cvt_pk_bf16_f32 v37, v37, s0
	v_cvt_pk_bf16_f32 v53, v53, s0
	v_cvt_pk_bf16_f32 v6, v6, s0
	v_cvt_pk_bf16_f32 v22, v22, s0
	v_cvt_pk_bf16_f32 v38, v38, s0
	v_cvt_pk_bf16_f32 v54, v54, s0
	v_cvt_pk_bf16_f32 v7, v7, s0
	v_cvt_pk_bf16_f32 v23, v23, s0
	v_cvt_pk_bf16_f32 v39, v39, s0
	v_cvt_pk_bf16_f32 v55, v55, s0
	global_store_short v[104:105], v0, off
	global_store_short v[104:105], v16, off offset:64
	global_store_short v[104:105], v32, off offset:128
	global_store_short v[104:105], v48, off offset:192
	global_store_short v[134:135], v1, off offset:-4096
	global_store_short v[128:129], v17, off offset:64
	global_store_short v[128:129], v33, off offset:128
	global_store_short v[128:129], v49, off offset:192
	global_store_short v[134:135], v2, off
	global_store_short v[134:135], v18, off offset:64
	global_store_short v[134:135], v34, off offset:128
	global_store_short v[134:135], v50, off offset:192
	global_store_short v[132:133], v3, off
	global_store_short v[132:133], v19, off offset:64
	global_store_short v[132:133], v35, off offset:128
	global_store_short v[132:133], v51, off offset:192
	global_store_short v[102:103], v4, off
	global_store_short v[102:103], v20, off offset:64
	global_store_short v[102:103], v36, off offset:128
	global_store_short v[102:103], v52, off offset:192
	global_store_short v[126:127], v5, off offset:-4096
	global_store_short v[130:131], v21, off offset:64
	global_store_short v[130:131], v37, off offset:128
	global_store_short v[130:131], v53, off offset:192
	global_store_short v[126:127], v6, off
	global_store_short v[126:127], v22, off offset:64
	global_store_short v[126:127], v38, off offset:128
	global_store_short v[126:127], v54, off offset:192
	global_store_short v[124:125], v7, off
	global_store_short v[124:125], v23, off offset:64
	global_store_short v[124:125], v39, off offset:128
	global_store_short v[124:125], v55, off offset:192
	global_load_ushort v7, v[108:109], off
	global_load_dword v16, v[100:101], off offset:64
	global_load_ushort v17, v[108:109], off offset:64
	global_load_ushort v18, v[108:109], off offset:128
	global_load_ushort v19, v[108:109], off offset:192
	global_load_ushort v20, v[114:115], off offset:-4096
	global_load_dwordx3 v[4:6], v[110:111], off offset:68
	global_load_ushort v21, v[112:113], off offset:64
	global_load_ushort v22, v[112:113], off offset:128
	global_load_ushort v23, v[112:113], off offset:192
	global_load_ushort v32, v[114:115], off
	global_load_ushort v33, v[114:115], off offset:64
	global_load_ushort v34, v[114:115], off offset:128
	global_load_ushort v35, v[114:115], off offset:192
	global_load_ushort v36, v[122:123], off
	global_load_ushort v37, v[122:123], off offset:64
	global_load_ushort v38, v[122:123], off offset:128
	global_load_ushort v39, v[122:123], off offset:192
	global_load_ushort v48, v[106:107], off
	global_load_dwordx4 v[0:3], v[100:101], off offset:96
	global_load_ushort v49, v[106:107], off offset:64
	global_load_ushort v50, v[106:107], off offset:128
	global_load_ushort v51, v[106:107], off offset:192
	global_load_ushort v52, v[118:119], off offset:-4096
	global_load_ushort v53, v[120:121], off offset:64
	global_load_ushort v54, v[120:121], off offset:128
	global_load_ushort v55, v[120:121], off offset:192
	global_load_ushort v100, v[118:119], off
	global_load_ushort v101, v[118:119], off offset:64
	global_load_ushort v102, v[118:119], off offset:128
	global_load_ushort v103, v[118:119], off offset:192
	global_load_ushort v104, v[116:117], off
	global_load_ushort v105, v[116:117], off offset:64
	global_load_ushort v110, v[116:117], off offset:128
	global_load_ushort v111, v[116:117], off offset:192
	s_waitcnt vmcnt(34)
; __device__ __forceinline__ unsigned cvtpk(float lo, float hi) { f32x2 v = {lo, hi}; bf16x2_t b = __builtin_convertvector(v, bf16x2_t); return __builtin_bit_cast(unsigned, b); }
; __device__ __forceinline__ float bf2f(bf16_t b) { return __uint_as_float(((unsigned)b) << 16); }
; __device__ __forceinline__ void spatial_unit(LAS unsigned char* lds, const Args& a, int b, int n, int ghalf, int tid, int wid, int lane) {
;     ...
; #pragma unroll
;         for (int hh2 = 0; hh2 < 2; ++hh2) {
;             bf16_t uv[8][4]; float bias[8];
; #pragma unroll
;             for (int ii = 0; ii < 8; ++ii) { const int i = hh2 * 8 + ii, il = ib * 32 + (i & 3) + 8 * (i >> 2) + 4 * h; bias[ii] = a.sg_b[g * 128 + il];
;                 const size_t off = (size_t)(tok0 + il) * DM + g * 256 + dbh * 128 + r;
; #pragma unroll
;                 for (int d = 0; d < 4; ++d) uv[ii][d] = Up[off + 32 * d]; }
;             asm volatile("" ::: "memory");
; #pragma unroll
;             for (int ii = 0; ii < 8; ++ii) { const int i = hh2 * 8 + ii, il = ib * 32 + (i & 3) + 8 * (i >> 2) + 4 * h;
;                 const size_t off = (size_t)(tok0 + il) * DM + g * 256 + dbh * 128 + r;
; #pragma unroll
;                 for (int d = 0; d < 4; ++d) Up[off + 32 * d] = (bf16_t)(cvtpk(bf2f(uv[ii][d]) * (acc[d][i] + bias[ii]), 0.f) & 0xffffu); }
;             asm volatile("" ::: "memory");
;         }
;         __syncthreads();
;     }
	v_lshlrev_b32_e32 v7, 16, v7
	s_waitcnt vmcnt(33)
	v_add_f32_e32 v8, v8, v16
	s_waitcnt vmcnt(32)
	v_lshlrev_b32_e32 v17, 16, v17
	v_add_f32_e32 v24, v24, v16
	s_waitcnt vmcnt(31)
	v_lshlrev_b32_e32 v18, 16, v18
	v_add_f32_e32 v40, v40, v16
	s_waitcnt vmcnt(30)
	v_lshlrev_b32_e32 v19, 16, v19
	v_add_f32_e32 v16, v56, v16
	s_waitcnt vmcnt(29)
	v_lshlrev_b32_e32 v20, 16, v20
	s_waitcnt vmcnt(28)
	v_add_f32_e32 v9, v9, v4
	s_waitcnt vmcnt(27)
	v_lshlrev_b32_e32 v21, 16, v21
	v_add_f32_e32 v25, v25, v4
	s_waitcnt vmcnt(26)
	v_lshlrev_b32_e32 v22, 16, v22
	v_add_f32_e32 v41, v41, v4
	s_waitcnt vmcnt(25)
	v_lshlrev_b32_e32 v23, 16, v23
	v_add_f32_e32 v4, v57, v4
	s_waitcnt vmcnt(24)
	v_lshlrev_b32_e32 v32, 16, v32
	v_add_f32_e32 v10, v10, v5
	s_waitcnt vmcnt(23)
	v_lshlrev_b32_e32 v33, 16, v33
	v_add_f32_e32 v26, v26, v5
	s_waitcnt vmcnt(22)
	v_lshlrev_b32_e32 v34, 16, v34
	v_add_f32_e32 v42, v42, v5
	s_waitcnt vmcnt(21)
	v_lshlrev_b32_e32 v35, 16, v35
	v_add_f32_e32 v5, v58, v5
	s_waitcnt vmcnt(20)
	v_lshlrev_b32_e32 v36, 16, v36
	v_add_f32_e32 v11, v11, v6
	s_waitcnt vmcnt(19)
	v_lshlrev_b32_e32 v37, 16, v37
	v_add_f32_e32 v27, v27, v6
	s_waitcnt vmcnt(18)
	v_lshlrev_b32_e32 v38, 16, v38
	v_add_f32_e32 v43, v43, v6
	s_waitcnt vmcnt(17)
	v_lshlrev_b32_e32 v39, 16, v39
	v_add_f32_e32 v6, v59, v6
	s_waitcnt vmcnt(16)
	v_lshlrev_b32_e32 v48, 16, v48
	s_waitcnt vmcnt(15)
	v_add_f32_e32 v12, v12, v0
	s_waitcnt vmcnt(14)
	v_lshlrev_b32_e32 v49, 16, v49
	v_add_f32_e32 v28, v28, v0
	s_waitcnt vmcnt(13)
	v_lshlrev_b32_e32 v50, 16, v50
	v_add_f32_e32 v44, v44, v0
	s_waitcnt vmcnt(12)
	v_lshlrev_b32_e32 v51, 16, v51
	v_add_f32_e32 v0, v60, v0
	s_waitcnt vmcnt(11)
	v_lshlrev_b32_e32 v52, 16, v52
	v_add_f32_e32 v13, v13, v1
	s_waitcnt vmcnt(10)
	v_lshlrev_b32_e32 v53, 16, v53
	v_add_f32_e32 v29, v29, v1
	s_waitcnt vmcnt(9)
	v_lshlrev_b32_e32 v54, 16, v54
	v_add_f32_e32 v45, v45, v1
	s_waitcnt vmcnt(8)
	v_lshlrev_b32_e32 v55, 16, v55
	v_add_f32_e32 v1, v61, v1
	s_waitcnt vmcnt(7)
	v_lshlrev_b32_e32 v56, 16, v100
	v_add_f32_e32 v14, v14, v2
	s_waitcnt vmcnt(6)
	v_lshlrev_b32_e32 v57, 16, v101
	v_add_f32_e32 v30, v30, v2
	s_waitcnt vmcnt(5)
	v_lshlrev_b32_e32 v58, 16, v102
	v_add_f32_e32 v46, v46, v2
	s_waitcnt vmcnt(4)
	v_lshlrev_b32_e32 v59, 16, v103
	v_add_f32_e32 v2, v62, v2
	s_waitcnt vmcnt(3)
	v_lshlrev_b32_e32 v60, 16, v104
	v_add_f32_e32 v15, v15, v3
	s_waitcnt vmcnt(2)
	v_lshlrev_b32_e32 v61, 16, v105
	v_add_f32_e32 v31, v31, v3
	s_waitcnt vmcnt(1)
	v_lshlrev_b32_e32 v62, 16, v110
	v_add_f32_e32 v47, v47, v3
	s_waitcnt vmcnt(0)
	v_lshlrev_b32_e32 v100, 16, v111
	v_add_f32_e32 v3, v63, v3
	v_mul_f32_e32 v7, v8, v7
	v_mul_f32_e32 v8, v24, v17
	v_mul_f32_e32 v17, v40, v18
	v_mul_f32_e32 v16, v16, v19
	v_mul_f32_e32 v9, v9, v20
	v_mul_f32_e32 v18, v25, v21
	v_mul_f32_e32 v19, v41, v22
	v_mul_f32_e32 v4, v4, v23
	v_mul_f32_e32 v10, v10, v32
	v_mul_f32_e32 v20, v26, v33
	v_mul_f32_e32 v21, v42, v34
	v_mul_f32_e32 v5, v5, v35
	v_mul_f32_e32 v11, v11, v36
	v_mul_f32_e32 v22, v27, v37
	v_mul_f32_e32 v23, v43, v38
	v_mul_f32_e32 v6, v6, v39
	v_mul_f32_e32 v12, v12, v48
	v_mul_f32_e32 v24, v28, v49
	v_mul_f32_e32 v25, v44, v50
	v_mul_f32_e32 v0, v0, v51
	v_mul_f32_e32 v13, v13, v52
	v_mul_f32_e32 v26, v29, v53
	v_mul_f32_e32 v27, v45, v54
	v_mul_f32_e32 v1, v1, v55
	v_mul_f32_e32 v14, v14, v56
	v_mul_f32_e32 v28, v30, v57
	v_mul_f32_e32 v29, v46, v58
	v_mul_f32_e32 v2, v2, v59
	v_mul_f32_e32 v15, v15, v60
	v_mul_f32_e32 v30, v31, v61
	v_mul_f32_e32 v31, v47, v62
	v_mul_f32_e32 v3, v3, v100
	v_cvt_pk_bf16_f32 v7, v7, s0
	v_cvt_pk_bf16_f32 v8, v8, s0
	v_cvt_pk_bf16_f32 v17, v17, s0
	v_cvt_pk_bf16_f32 v16, v16, s0
	v_cvt_pk_bf16_f32 v9, v9, s0
	v_cvt_pk_bf16_f32 v18, v18, s0
	v_cvt_pk_bf16_f32 v19, v19, s0
	v_cvt_pk_bf16_f32 v4, v4, s0
	v_cvt_pk_bf16_f32 v10, v10, s0
	v_cvt_pk_bf16_f32 v20, v20, s0
	v_cvt_pk_bf16_f32 v21, v21, s0
	v_cvt_pk_bf16_f32 v5, v5, s0
	v_cvt_pk_bf16_f32 v11, v11, s0
	v_cvt_pk_bf16_f32 v22, v22, s0
	v_cvt_pk_bf16_f32 v23, v23, s0
	v_cvt_pk_bf16_f32 v6, v6, s0
	v_cvt_pk_bf16_f32 v12, v12, s0
	v_cvt_pk_bf16_f32 v24, v24, s0
	v_cvt_pk_bf16_f32 v25, v25, s0
	v_cvt_pk_bf16_f32 v0, v0, s0
	v_cvt_pk_bf16_f32 v13, v13, s0
	v_cvt_pk_bf16_f32 v26, v26, s0
	v_cvt_pk_bf16_f32 v27, v27, s0
	v_cvt_pk_bf16_f32 v1, v1, s0
	v_cvt_pk_bf16_f32 v14, v14, s0
	v_cvt_pk_bf16_f32 v28, v28, s0
	v_cvt_pk_bf16_f32 v29, v29, s0
	v_cvt_pk_bf16_f32 v2, v2, s0
	v_cvt_pk_bf16_f32 v15, v15, s0
	v_cvt_pk_bf16_f32 v30, v30, s0
	v_cvt_pk_bf16_f32 v31, v31, s0
	v_cvt_pk_bf16_f32 v3, v3, s0
	global_store_short v[108:109], v7, off
	global_store_short v[108:109], v8, off offset:64
	global_store_short v[108:109], v17, off offset:128
	global_store_short v[108:109], v16, off offset:192
	global_store_short v[114:115], v9, off offset:-4096
	global_store_short v[112:113], v18, off offset:64
	global_store_short v[112:113], v19, off offset:128
	global_store_short v[112:113], v4, off offset:192
	global_store_short v[114:115], v10, off
	global_store_short v[114:115], v20, off offset:64
	global_store_short v[114:115], v21, off offset:128
	global_store_short v[114:115], v5, off offset:192
	global_store_short v[122:123], v11, off
	global_store_short v[122:123], v22, off offset:64
	global_store_short v[122:123], v23, off offset:128
	global_store_short v[122:123], v6, off offset:192
	global_store_short v[106:107], v12, off
	global_store_short v[106:107], v24, off offset:64
	global_store_short v[106:107], v25, off offset:128
	global_store_short v[106:107], v0, off offset:192
	global_store_short v[118:119], v13, off offset:-4096
	global_store_short v[120:121], v26, off offset:64
	global_store_short v[120:121], v27, off offset:128
	global_store_short v[120:121], v1, off offset:192
	global_store_short v[118:119], v14, off
	global_store_short v[118:119], v28, off offset:64
	global_store_short v[118:119], v29, off offset:128
	global_store_short v[118:119], v2, off offset:192
	global_store_short v[116:117], v15, off
	global_store_short v[116:117], v30, off offset:64
	global_store_short v[116:117], v31, off offset:128
	global_store_short v[116:117], v3, off offset:192
	s_barrier
	s_cbranch_scc1 .LBB0_520
	s_add_i32 s65, s65, s30
	s_add_i32 s15, s15, s22
	s_add_i32 s23, s23, s33
	s_cmpk_gt_i32 s65, 0xff
	s_cbranch_scc0 .LBB0_509
